# token_a: the 8-lane paired sum reduction via DPP (quad_perm, row_half_mirror) instead of three pairs of ds_bpermute round trips, same pairing order; on top of the token_c/rmsnorm DPP versions
# speedup vs baseline: 1.0071x; 1.0071x over previous
; DI unsigned pk2(float a, float b) { f32x2 v = {a, b}; return __builtin_bit_cast(unsigned, __builtin_convertvector(v, bf16x2)); }
; DI float bflo(unsigned u) { return __uint_as_float(u << 16); }
; DI float bfhi(unsigned u) { return __uint_as_float(u & 0xffff0000u); }
; DI void phase_token_a(const Params& P, int layer, char* smem) {
;     ...
;   for (int t = blockIdx.x * 4 + w; t < T_; t += gridDim.x * 4) {
;     unsigned short* zr = Z + (size_t)t * ZLD;
; #pragma unroll
;     for (int which = 0; which < 2; ++which) {
;       const float* g = which ? gk : gq;
;       u32x4* p = (u32x4*)(zr + (which ? C_KA : C_QA) + lane * 8);
;       u32x4 u = *p;
;       float f[8] = {bflo(u.x), bfhi(u.x), bflo(u.y), bfhi(u.y), bflo(u.z), bfhi(u.z), bflo(u.w), bfhi(u.w)};
;       float ss = 0.f;
; #pragma unroll
;       for (int j = 0; j < 8; ++j) ss += f[j] * f[j];
;       ss += __shfl_xor(ss, 1); ss += __shfl_xor(ss, 2); ss += __shfl_xor(ss, 4);
;       const float r = rsqrtf(ss * (1.f / 64) + EPS);
;       const int c0 = (lane & 7) * 8;
; #pragma unroll
;       for (int j = 0; j < 8; ++j) f[j] = f[j] * r * g[c0 + j];
;       u.x = pk2(f[0], f[1]); u.y = pk2(f[2], f[3]); u.z = pk2(f[4], f[5]); u.w = pk2(f[6], f[7]);
;       *p = u;
;     }
;     {
;       unsigned* p = (unsigned*)(zr + C_CQ + lane * 6);
;       unsigned u0 = p[0], u1 = p[1], u2 = p[2];
;       float f[6] = {bflo(u0), bfhi(u0), bflo(u1), bfhi(u1), bflo(u2), bfhi(u2)};
;       float ss = 0.f;
; #pragma unroll
;       for (int j = 0; j < 6; ++j) ss += f[j] * f[j];
;       ss = wave_sum(ss);
;       const float r = rsqrtf(ss * (1.f / 384) + EPS);
; #pragma unroll
;       for (int j = 0; j < 6; ++j) f[j] = f[j] * r * gcq[lane * 6 + j];
;       p[0] = pk2(f[0], f[1]); p[1] = pk2(f[2], f[3]); p[2] = pk2(f[4], f[5]);
;     }
;     {
;       u32x2* p = (u32x2*)(zr + C_CKV + lane * 4);
;       u32x2 u = *p;
;       float f[4] = {bflo(u.x), bfhi(u.x), bflo(u.y), bfhi(u.y)};
;       float ss = f[0] * f[0] + f[1] * f[1] + f[2] * f[2] + f[3] * f[3];
;       ss = wave_sum(ss);
.LBB0_422:
	v_mov_b64_e32 v[0:1], s[86:87]
	v_mad_i64_i32 v[22:23], s[0:1], v36, s33, v[0:1]
	v_lshl_add_u64 v[26:27], v[22:23], 0, v[136:137]
	global_load_dwordx4 v[44:47], v[26:27], off
	global_load_dwordx4 v[0:3], v[8:9], off offset:16
	global_load_dwordx4 v[4:7], v[8:9], off
	s_mov_b32 s0, 0x358637bd
	v_mov_b32_e32 v21, v137
	s_waitcnt vmcnt(0)
	v_lshlrev_b32_e32 v28, 16, v47
	v_and_b32_e32 v29, 0xffff0000, v47
	v_lshlrev_b32_e32 v30, 16, v46
	v_and_b32_e32 v31, 0xffff0000, v46
	v_lshlrev_b32_e32 v32, 16, v45
	v_and_b32_e32 v33, 0xffff0000, v45
	v_lshlrev_b32_e32 v34, 16, v44
	v_and_b32_e32 v35, 0xffff0000, v44
	global_load_dwordx4 v[44:47], v[26:27], off offset:1024
	v_pk_mul_f32 v[52:53], v[34:35], v[34:35]
	v_pk_mul_f32 v[50:51], v[32:33], v[32:33]
	v_mov_b32_e32 v67, v52
	v_pk_mul_f32 v[48:49], v[30:31], v[30:31]
	v_pk_mul_f32 v[24:25], v[28:29], v[28:29]
	s_waitcnt vmcnt(0)
	v_lshlrev_b32_e32 v64, 16, v44
	v_and_b32_e32 v65, 0xffff0000, v44
	v_lshlrev_b32_e32 v60, 16, v45
	v_and_b32_e32 v61, 0xffff0000, v45
	v_pk_mul_f32 v[44:45], v[64:65], v[64:65]
	v_pk_mul_f32 v[62:63], v[60:61], v[60:61]
	v_mov_b32_e32 v66, v44
	v_mov_b32_e32 v52, v45
	v_lshlrev_b32_e32 v58, 16, v46
	v_and_b32_e32 v59, 0xffff0000, v46
	v_pk_add_f32 v[44:45], v[66:67], v[52:53]
	v_mov_b32_e32 v52, v62
	v_mov_b32_e32 v53, v50
	v_lshlrev_b32_e32 v54, 16, v47
	v_and_b32_e32 v55, 0xffff0000, v47
	v_pk_mul_f32 v[46:47], v[58:59], v[58:59]
	v_pk_add_f32 v[44:45], v[52:53], v[44:45]
	v_mov_b32_e32 v50, v63
	v_pk_add_f32 v[44:45], v[50:51], v[44:45]
	v_mov_b32_e32 v50, v46
	v_mov_b32_e32 v51, v48
	v_pk_mul_f32 v[56:57], v[54:55], v[54:55]
	v_pk_add_f32 v[44:45], v[50:51], v[44:45]
	v_mov_b32_e32 v48, v47
	v_pk_add_f32 v[44:45], v[48:49], v[44:45]
	v_mov_b32_e32 v46, v56
	v_mov_b32_e32 v47, v24
	v_pk_add_f32 v[44:45], v[46:47], v[44:45]
	v_mov_b32_e32 v24, v57
	v_pk_add_f32 v[24:25], v[24:25], v[44:45]
	s_waitcnt lgkmcnt(0)
	s_nop 1
	v_add_f32_dpp v24, v24, v24 quad_perm:[1,0,3,2] row_mask:0xf bank_mask:0xf
	v_add_f32_dpp v25, v25, v25 quad_perm:[1,0,3,2] row_mask:0xf bank_mask:0xf
	s_nop 1
	v_add_f32_dpp v24, v24, v24 quad_perm:[2,3,0,1] row_mask:0xf bank_mask:0xf
	v_add_f32_dpp v25, v25, v25 quad_perm:[2,3,0,1] row_mask:0xf bank_mask:0xf
	s_nop 1
	v_add_f32_dpp v44, v24, v24 row_half_mirror row_mask:0xf bank_mask:0xf
	v_add_f32_dpp v45, v25, v25 row_half_mirror row_mask:0xf bank_mask:0xf
	v_mov_b64_e32 v[24:25], s[0:1]
	s_mov_b32 s0, 0x3c800000
	v_pk_fma_f32 v[44:45], v[44:45], s[0:1], v[24:25] op_sel_hi:[1,0,0]
	s_nop 0
	v_mul_f32_e32 v17, 0x4b800000, v45
	v_cmp_gt_f32_e64 s[0:1], s6, v45
	v_cmp_gt_f32_e32 vcc, s6, v44
	s_nop 0
	v_cndmask_b32_e64 v17, v45, v17, s[0:1]
	v_rsq_f32_e32 v17, v17
	s_nop 0
	v_mul_f32_e32 v19, 0x45800000, v17
	v_cndmask_b32_e64 v46, v17, v19, s[0:1]
	v_mul_f32_e32 v46, 0x3e38aa3b, v46
	v_pk_mul_f32 v[30:31], v[46:47], v[30:31] op_sel_hi:[0,1]
	v_pk_mul_f32 v[34:35], v[46:47], v[34:35] op_sel_hi:[0,1]
	v_pk_mul_f32 v[32:33], v[46:47], v[32:33] op_sel_hi:[0,1]
	v_pk_mul_f32 v[30:31], v[0:1], v[30:31]
	v_pk_mul_f32 v[0:1], v[46:47], v[28:29] op_sel_hi:[0,1]
	v_pk_mul_f32 v[4:5], v[4:5], v[34:35]
	v_pk_mul_f32 v[6:7], v[6:7], v[32:33]
	v_pk_mul_f32 v[28:29], v[2:3], v[0:1]
	v_cvt_pk_bf16_f32 v0, v4, v5
	v_cvt_pk_bf16_f32 v1, v6, v7
	v_cvt_pk_bf16_f32 v2, v30, v31
	v_cvt_pk_bf16_f32 v3, v28, v29
	global_store_dwordx4 v[26:27], v[0:3], off
	global_load_dwordx4 v[0:3], v[10:11], off offset:16
	s_nop 0
	global_load_dwordx4 v[4:7], v[10:11], off
	v_mul_f32_e32 v17, 0x4b800000, v44
	v_cndmask_b32_e32 v17, v44, v17, vcc
	v_rsq_f32_e32 v17, v17
	s_mov_b32 s0, 0x3b800000
	s_mov_b32 s1, 0x3b2aaaab
	v_mul_f32_e32 v19, 0x45800000, v17
	v_cndmask_b32_e32 v28, v17, v19, vcc
	v_pk_mul_f32 v[30:31], v[28:29], v[64:65] op_sel_hi:[0,1]
	v_mov_b32_e32 v17, v137
	v_mov_b32_e32 v19, v137
	s_waitcnt vmcnt(0)
	v_pk_mul_f32 v[4:5], v[4:5], v[30:31]
	v_pk_mul_f32 v[30:31], v[28:29], v[60:61] op_sel_hi:[0,1]
	v_pk_mul_f32 v[6:7], v[6:7], v[30:31]
	v_pk_mul_f32 v[30:31], v[28:29], v[58:59] op_sel_hi:[0,1]
	v_pk_mul_f32 v[30:31], v[0:1], v[30:31]
	v_pk_mul_f32 v[0:1], v[28:29], v[54:55] op_sel_hi:[0,1]
	v_pk_mul_f32 v[28:29], v[2:3], v[0:1]
	v_cvt_pk_bf16_f32 v0, v4, v5
	v_cvt_pk_bf16_f32 v1, v6, v7
	v_cvt_pk_bf16_f32 v2, v30, v31
	v_cvt_pk_bf16_f32 v3, v28, v29
	global_store_dwordx4 v[26:27], v[0:3], off offset:1024
	s_nop 1
	v_lshl_add_u64 v[0:1], v[22:23], 0, v[16:17]
	v_add_co_u32_e32 v26, vcc, s3, v0
	s_nop 1
	v_addc_co_u32_e32 v27, vcc, 0, v1, vcc
	global_load_dwordx3 v[0:2], v[26:27], off offset:144
	s_waitcnt vmcnt(0)
	v_and_b32_e32 v29, 0xffff0000, v0
	v_lshlrev_b32_e32 v28, 16, v0
	v_mul_f32_e32 v4, v29, v29
	v_lshlrev_b32_e32 v30, 16, v1
	v_and_b32_e32 v31, 0xffff0000, v1
	v_pk_fma_f32 v[4:5], v[28:29], v[28:29], v[4:5] op_sel_hi:[1,1,0]
	v_lshlrev_b32_e32 v32, 16, v2
	v_pk_fma_f32 v[48:49], v[30:31], v[30:31], v[4:5]
	v_lshl_add_u64 v[4:5], v[22:23], 0, v[18:19]
	v_add_co_u32_e32 v50, vcc, s3, v4
	v_and_b32_e32 v33, 0xffff0000, v2
	s_nop 0
	v_addc_co_u32_e32 v51, vcc, 0, v5, vcc
	global_load_dwordx2 v[46:47], v[12:13], off offset:16
	global_load_dwordx4 v[0:3], v[12:13], off
	global_load_dwordx2 v[4:5], v[50:51], off offset:912
	v_pk_mul_f32 v[44:45], v[30:31], v[30:31]
	v_pk_mul_f32 v[34:35], v[32:33], v[32:33]
	s_waitcnt vmcnt(0)
	v_lshlrev_b32_e32 v52, 16, v5
	v_and_b32_e32 v53, 0xffff0000, v5
	v_lshlrev_b32_e32 v56, 16, v4
	v_and_b32_e32 v57, 0xffff0000, v4
	global_load_dwordx4 v[4:7], v[14:15], off
	v_pk_mul_f32 v[58:59], v[56:57], v[56:57]
	v_pk_mul_f32 v[54:55], v[52:53], v[52:53]
	v_mov_b32_e32 v44, v58
	v_pk_mov_b32 v[48:49], v[58:59], v[48:49] op_sel:[1,0]
	s_nop 0
	v_pk_add_f32 v[44:45], v[44:45], v[48:49]
	v_mov_b32_e32 v48, v54
	v_mov_b32_e32 v49, v34
	v_pk_add_f32 v[44:45], v[48:49], v[44:45]
	v_mov_b32_e32 v34, v55
	v_pk_add_f32 v[34:35], v[34:35], v[44:45]
	ds_bpermute_b32 v45, v40, v35
	ds_bpermute_b32 v44, v40, v34
	s_waitcnt lgkmcnt(0)
; DI unsigned pk2(float a, float b) { f32x2 v = {a, b}; return __builtin_bit_cast(unsigned, __builtin_convertvector(v, bf16x2)); }
; DI float bf2f(unsigned short u) { return __uint_as_float(((unsigned)u) << 16); }
; DI float bflo(unsigned u) { return __uint_as_float(u << 16); }
; DI float bfhi(unsigned u) { return __uint_as_float(u & 0xffff0000u); }
; DI void phase_token_a(const Params& P, int layer, char* smem) {
;     ...
;       ss = wave_sum(ss);
;       const float r = rsqrtf(ss * (1.f / 384) + EPS);
; #pragma unroll
;       for (int j = 0; j < 6; ++j) f[j] = f[j] * r * gcq[lane * 6 + j];
;       p[0] = pk2(f[0], f[1]); p[1] = pk2(f[2], f[3]); p[2] = pk2(f[4], f[5]);
;     }
;     {
;       u32x2* p = (u32x2*)(zr + C_CKV + lane * 4);
;       u32x2 u = *p;
;       float f[4] = {bflo(u.x), bfhi(u.x), bflo(u.y), bfhi(u.y)};
;       float ss = f[0] * f[0] + f[1] * f[1] + f[2] * f[2] + f[3] * f[3];
;       ss = wave_sum(ss);
;       const float r = rsqrtf(ss * (1.f / 256) + EPS);
; #pragma unroll
;       for (int j = 0; j < 4; ++j) f[j] = f[j] * r * gckv[lane * 4 + j];
;       u.x = pk2(f[0], f[1]); u.y = pk2(f[2], f[3]);
;       *p = u;
;     }
;     {
;       const int i = lane & 15;
;       const float x1 = bf2f(zr[C_KR + i]), x2 = bf2f(zr[C_KR + 16 + i]);
;       const float inv = powf(10000.f, -(float)i / 16.f);
;       const float ang = (float)(t % S_) * inv;
;       float sn, cs;
;       sincosf(ang, &sn, &cs);
	v_pk_add_f32 v[34:35], v[34:35], v[44:45]
	ds_bpermute_b32 v45, v41, v35
	ds_bpermute_b32 v44, v41, v34
	s_waitcnt lgkmcnt(0)
	v_pk_add_f32 v[34:35], v[34:35], v[44:45]
	ds_bpermute_b32 v45, v42, v35
	ds_bpermute_b32 v44, v42, v34
	s_waitcnt lgkmcnt(0)
	v_pk_add_f32 v[34:35], v[34:35], v[44:45]
	ds_bpermute_b32 v45, v39, v35
	ds_bpermute_b32 v44, v39, v34
	s_waitcnt lgkmcnt(0)
	v_pk_add_f32 v[34:35], v[34:35], v[44:45]
	ds_bpermute_b32 v45, v38, v35
	ds_bpermute_b32 v44, v38, v34
	s_waitcnt lgkmcnt(0)
	v_pk_add_f32 v[34:35], v[34:35], v[44:45]
	ds_bpermute_b32 v45, v37, v35
	ds_bpermute_b32 v44, v37, v34
	s_waitcnt lgkmcnt(0)
	v_pk_add_f32 v[34:35], v[34:35], v[44:45]
	s_nop 0
	v_pk_fma_f32 v[24:25], v[34:35], s[0:1], v[24:25] op_sel_hi:[1,1,0]
	s_nop 0
	v_mul_f32_e32 v17, 0x4b800000, v25
	v_cmp_gt_f32_e64 s[0:1], s6, v25
	v_cmp_gt_f32_e32 vcc, s6, v24
	s_nop 0
	v_cndmask_b32_e64 v17, v25, v17, s[0:1]
	v_rsq_f32_e32 v17, v17
	s_nop 0
	v_mul_f32_e32 v19, 0x45800000, v17
	v_cndmask_b32_e64 v34, v17, v19, s[0:1]
	v_pk_mul_f32 v[28:29], v[34:35], v[28:29] op_sel_hi:[0,1]
	v_pk_mul_f32 v[0:1], v[0:1], v[28:29]
	v_pk_mul_f32 v[28:29], v[34:35], v[30:31] op_sel_hi:[0,1]
	v_pk_mul_f32 v[2:3], v[2:3], v[28:29]
	v_pk_mul_f32 v[28:29], v[34:35], v[32:33] op_sel_hi:[0,1]
	v_pk_mul_f32 v[28:29], v[46:47], v[28:29]
	v_cvt_pk_bf16_f32 v0, v0, v1
	v_cvt_pk_bf16_f32 v1, v2, v3
	v_cvt_pk_bf16_f32 v2, v28, v29
	global_store_dwordx3 v[26:27], v[0:2], off offset:144
	s_nop 1
	v_mul_f32_e32 v0, 0x4b800000, v24
	v_cndmask_b32_e32 v0, v24, v0, vcc
	v_rsq_f32_e32 v0, v0
	s_nop 0
	v_mul_f32_e32 v1, 0x45800000, v0
	v_cndmask_b32_e32 v0, v0, v1, vcc
	v_pk_mul_f32 v[2:3], v[0:1], v[56:57] op_sel_hi:[0,1]
	v_pk_mul_f32 v[0:1], v[0:1], v[52:53] op_sel_hi:[0,1]
	s_waitcnt vmcnt(1)
	v_pk_mul_f32 v[2:3], v[4:5], v[2:3]
	v_pk_mul_f32 v[0:1], v[6:7], v[0:1]
	v_cvt_pk_bf16_f32 v2, v2, v3
	v_cvt_pk_bf16_f32 v3, v0, v1
	v_lshl_add_u64 v[0:1], v[22:23], 0, v[20:21]
	v_add_co_u32_e32 v4, vcc, s3, v0
	global_store_dwordx2 v[50:51], v[2:3], off offset:912
	s_nop 0
	v_addc_co_u32_e32 v5, vcc, 0, v1, vcc
	global_load_ushort v2, v[4:5], off offset:1424
	global_load_ushort v3, v[4:5], off offset:1456
	v_ashrrev_i32_e32 v4, 31, v36
	v_lshrrev_b32_e32 v4, 18, v4
	v_add_u32_e32 v4, v36, v4
	v_and_b32_e32 v4, 0xffffc000, v4
	v_sub_u32_e32 v4, v36, v4
	v_cvt_f32_i32_e32 v4, v4
	v_mul_f32_e32 v4, v43, v4
	v_and_b32_e32 v5, 0x7fffffff, v4
	v_cmp_nlt_f32_e64 s[0:1], |v4|, s18
	s_and_saveexec_b64 s[14:15], s[0:1]
	s_xor_b64 s[14:15], exec, s[14:15]
	s_cbranch_execz .LBB0_425
	v_lshrrev_b32_e32 v6, 23, v5
	v_add_u32_e32 v6, 0xffffff88, v6
	v_cmp_lt_u32_e32 vcc, 63, v6
	v_mov_b32_e32 v23, v137
	v_mov_b32_e32 v25, v137
	v_cndmask_b32_e32 v7, 0, v167, vcc
	v_add_u32_e32 v6, v7, v6
	v_cmp_lt_u32_e64 s[0:1], 31, v6
	v_mov_b32_e32 v27, v137
	v_mov_b32_e32 v29, v137
	v_cndmask_b32_e64 v7, 0, v197, s[0:1]
	v_add_u32_e32 v6, v7, v6
	v_cmp_lt_u32_e64 s[42:43], 31, v6
	v_mov_b32_e32 v31, v137
	v_mov_b32_e32 v33, v137
	v_cndmask_b32_e64 v7, 0, v197, s[42:43]
	v_add_u32_e32 v17, v7, v6
	v_and_b32_e32 v6, 0x7fffff, v5
	v_or_b32_e32 v19, 0x800000, v6
	v_mad_u64_u32 v[6:7], s[16:17], v19, s19, 0
	v_mov_b32_e32 v22, v7
	v_mad_u64_u32 v[22:23], s[16:17], v19, s20, v[22:23]
	v_mov_b32_e32 v24, v23
	v_mad_u64_u32 v[24:25], s[16:17], v19, s21, v[24:25]
	v_mov_b32_e32 v26, v25
	v_mad_u64_u32 v[26:27], s[16:17], v19, s22, v[26:27]
	v_mov_b32_e32 v28, v27
	v_mad_u64_u32 v[28:29], s[16:17], v19, s23, v[28:29]
	v_mov_b32_e32 v30, v29
	v_mad_u64_u32 v[30:31], s[16:17], v19, s26, v[30:31]
	v_mov_b32_e32 v32, v31
	v_mad_u64_u32 v[32:33], s[16:17], v19, s28, v[32:33]
	v_cndmask_b32_e32 v7, v30, v26, vcc
	v_cndmask_b32_e32 v19, v32, v28, vcc
	v_cndmask_b32_e32 v23, v33, v30, vcc
	v_cndmask_b32_e64 v21, v19, v7, s[0:1]
	v_cndmask_b32_e64 v19, v23, v19, s[0:1]
	v_cndmask_b32_e32 v23, v28, v24, vcc
	v_cndmask_b32_e64 v7, v7, v23, s[0:1]
	v_cndmask_b32_e64 v19, v19, v21, s[42:43]
	v_cndmask_b32_e64 v21, v21, v7, s[42:43]
	v_sub_u32_e32 v25, 32, v17
	v_alignbit_b32 v27, v19, v21, v25
	v_cmp_eq_u32_e64 s[44:45], 0, v17
	v_cndmask_b32_e32 v6, v24, v6, vcc
	s_nop 0
	v_cndmask_b32_e64 v17, v27, v19, s[44:45]
	v_cndmask_b32_e32 v19, v26, v22, vcc
	v_cndmask_b32_e64 v22, v23, v19, s[0:1]
	v_cndmask_b32_e64 v7, v7, v22, s[42:43]
	v_alignbit_b32 v23, v21, v7, v25
	v_cndmask_b32_e64 v6, v19, v6, s[0:1]
	v_cndmask_b32_e64 v21, v23, v21, s[44:45]
	v_bfe_u32 v27, v17, 29, 1
	v_cndmask_b32_e64 v6, v22, v6, s[42:43]
	v_alignbit_b32 v23, v17, v21, 30
	v_sub_u32_e32 v28, 0, v27
	v_alignbit_b32 v19, v7, v6, v25
	v_xor_b32_e32 v23, v23, v28
	v_cndmask_b32_e64 v7, v19, v7, s[44:45]
	v_alignbit_b32 v19, v21, v7, 30
	v_ffbh_u32_e32 v21, v23
	v_min_u32_e32 v21, 32, v21
	v_alignbit_b32 v6, v7, v6, 30
	v_xor_b32_e32 v19, v19, v28
	v_sub_u32_e32 v22, 31, v21
	v_xor_b32_e32 v6, v6, v28
	v_alignbit_b32 v23, v23, v19, v22
	v_alignbit_b32 v6, v19, v6, v22
	v_alignbit_b32 v7, v23, v6, 9
	v_ffbh_u32_e32 v19, v7
	v_min_u32_e32 v19, 32, v19
	v_lshrrev_b32_e32 v26, 29, v17
	v_not_b32_e32 v22, v19
	v_alignbit_b32 v6, v7, v6, v22
	v_lshlrev_b32_e32 v7, 31, v26
	v_or_b32_e32 v22, 0x33000000, v7
	v_add_lshl_u32 v19, v19, v21, 23
	v_lshrrev_b32_e32 v6, 9, v6
	v_sub_u32_e32 v19, v22, v19
	v_or_b32_e32 v7, 0.5, v7
	v_lshlrev_b32_e32 v21, 23, v21
	v_or_b32_e32 v6, v19, v6
	v_lshrrev_b32_e32 v19, 9, v23
	v_sub_u32_e32 v7, v7, v21
	v_or_b32_e32 v7, v19, v7
	v_mul_f32_e32 v19, 0x3fc90fda, v7
	v_fma_f32 v21, v7, s29, -v19
	v_fmac_f32_e32 v21, 0x33a22168, v7
	v_fmac_f32_e32 v21, 0x3fc90fda, v6
	v_lshrrev_b32_e32 v7, 30, v17
	v_add_f32_e32 v6, v19, v21
	v_add_u32_e32 v7, v27, v7
	s_andn2_saveexec_b64 s[0:1], s[14:15]
	s_cbranch_execnz .LBB0_426
